# phase 6: static first work item per WG + scan task remap so the 8 column slices of one head share an XCD L2
# speedup vs baseline: 1.0067x; 1.0067x over previous
; #define TIDX opaque_tid()
; __device__ __forceinline__ void lds_barrier() { asm volatile("s_waitcnt lgkmcnt(0)\n\ts_barrier" ::: "memory"); }
; __device__ __forceinline__ int fetch_item(unsigned* ctr, unsigned char* lds) {
;     volatile int* slot = (volatile int*)(lds + DYN_LDS - 16);
;     lds_barrier();
;     if (TIDX == 0) *slot = (int)atomicAdd(ctr, 1u);
;     lds_barrier();
;     const int v = *slot;
;     return __builtin_amdgcn_readfirstlane(v);
;     ...
;     if (k == 6) {
;         while (true) {
;             const int it = fetch_item(ctl + seq, lds);
;             if (it >= 128 + 160 + 128 + 384) break;
;             if (it < 128) { if (sub & 2) compress_item(a, l, it, lds, ctl + 64 + seq); }
.LBB0_218:
	s_andn2_b64 vcc, exec, s[2:3]
	s_cbranch_vccnz .LBB0_593
	v_readlane_b32 s2, v254, 0
	s_waitcnt vmcnt(3)
	v_mov_b32_e32 v0, v224
	s_mov_b32 s2, s84
	s_mov_b64 s[2:3], s[0:1]
	s_load_dwordx2 s[2:3], s[2:3], 0xd0
	s_mov_b64 s[14:15], 0
	s_waitcnt lgkmcnt(0)
	s_add_u32 s14, s2, s14
	s_addc_u32 s15, s3, s15
	v_readlane_b32 s2, v255, 28
	v_readlane_b32 s3, v255, 29
	s_mov_b32 s16, s2
	s_ashr_i32 s17, s2, 31
	v_writelane_b32 v255, s2, 28
	s_ashr_i32 s13, s12, 31
	s_lshl_b64 s[16:17], s[16:17], 14
	v_writelane_b32 v255, s3, 29
	s_lshl_b64 s[2:3], s[12:13], 2
	s_add_u32 s18, s14, s2
	s_addc_u32 s19, s15, s3
	s_mov_b32 s100, 1
	s_branch .LBB0_223

; #define TIDX opaque_tid()
; __device__ __forceinline__ void lds_barrier() { asm volatile("s_waitcnt lgkmcnt(0)\n\ts_barrier" ::: "memory"); }
; __device__ __forceinline__ int fetch_item(unsigned* ctr, unsigned char* lds) {
;     volatile int* slot = (volatile int*)(lds + DYN_LDS - 16);
;     lds_barrier();
;     if (TIDX == 0) *slot = (int)atomicAdd(ctr, 1u);
;     lds_barrier();
;     const int v = *slot;
;     return __builtin_amdgcn_readfirstlane(v);
;     ...
;             const int it = fetch_item(ctl + seq, lds);
.LBB0_223:
	s_waitcnt lgkmcnt(0)
	s_barrier
	s_waitcnt vmcnt(3)
	v_mov_b32_e32 v0, v224
	s_nop 0
	v_cmp_eq_u32_e32 vcc, 0, v0
	s_and_saveexec_b64 s[2:3], vcc
	s_cbranch_execz .LBB0_225
	s_cmp_eq_u32 s100, 0
	s_cbranch_scc1 .Lp6f_dyn
	v_readlane_b32 s13, v254, 0
	s_mov_b32 s100, 0
	s_nop 1
	v_mov_b32_e32 v2, s13
	s_branch .Lp6f_got
.Lp6f_dyn:
	global_atomic_add v2, v215, v225, s[18:19] sc0
	s_waitcnt vmcnt(0)
	v_add_u32_e32 v2, s84, v2
.Lp6f_got:
	s_add_i32 s13, 0, 0x22ff0
	s_mov_b64 s[14:15], src_shared_base
	s_cmp_lg_u32 s13, -1
	s_cselect_b32 s13, s13, 0
	s_cselect_b32 s14, s15, 0
	v_mov_b32_e32 v0, s13
	v_mov_b32_e32 v1, s14
	s_waitcnt vmcnt(0)
	flat_store_dword v[0:1], v2 sc0 sc1
	s_waitcnt vmcnt(0)

; #define TIDX opaque_tid()
; template <int TYPE>
; __device__ __forceinline__ void scan_task(const Args& a, int task, unsigned char* lds) {
;     const int bh = task >> 3, es = task & 7, e0 = es * 16, b = bh / 5, h = bh % 5;
;     const int tid = TIDX, w = __builtin_amdgcn_readfirstlane(tid >> 6), lane = tid & 63, fr = lane & 15, fq = lane >> 4;
;     ...
;             else if (it < 288) { if (sub & 1) { if (it - 128 < 80) scan_task<0>(a, it - 128, lds); else scan_task<1>(a, it - 208, lds); } }
.LBB0_525:
	s_sub_u32 s14, s13, 128
	s_cmpk_gt_u32 s14, 127
	s_cbranch_scc1 .Lscan_noremap
	s_lshr_b32 s15, s14, 6
	s_lshl_b32 s15, s15, 3
	s_and_b32 s20, s14, 7
	s_add_u32 s15, s15, s20
	s_lshl_b32 s15, s15, 3
	s_bfe_u32 s20, s14, 0x30003
	s_add_u32 s15, s15, s20
	s_add_u32 s13, s15, 128
